# P6 hand-off: L2 write-back issued in front of the y_off write-through stores (overlaps their acknowledgements) instead of behind their drain; on top of the early acquire invalidates
# baseline (speedup 1.0000x reference)
; __device__ __forceinline__ int crow(int i, int hi) { return (i & 3) + 8 * (i >> 2) + 4 * hi; }
; __device__ __forceinline__ void yoff_unit(const float* d_skip, const float* gnorm, LAS unsigned char* ldsb, int unit, const bf16* XACT, const bf16* PROJ, const float* ACS, const bf16* PREVT,
;                                           const bf16* YD, bf16* MIXB, int lane, int wave) {
;     ...
;     __syncthreads();
; #pragma unroll
;     for (int i = 0; i < 16; ++i) { const int l = 32 * lt + crow(i, hi); ssq[i] = rsqrtf((TAB[l] + TAB[128 + l]) * (1.f / 256.f) + EPS); }
; #pragma unroll
;     for (int hsel = 0; hsel < 2; ++hsel) {
;         const unsigned col = (unsigned)((g * 4 + 2 * hpair + hsel) * 64 + 2 * r); const float gn0 = gnorm[col], gn1 = gnorm[col + 1];
;         const unsigned voB = (tb * 1024u + 512u + col) * 2u;
; #pragma unroll
;         for (int i = 0; i < 16; ++i) { const unsigned w = ypk[hsel][i]; const float sn = ssq[i];
;             __builtin_amdgcn_raw_buffer_store_b32(pkbf(__uint_as_float(w << 16) * sn * gn0, __uint_as_float(w & 0xffff0000u) * sn * gn1), rsB, (int)voB, ((i & 3) + 8 * (i >> 2)) * 2048, 16); }
.LBB0_468:
	s_or_b64 exec, exec, s[4:5]
	v_cvt_pk_bf16_f32 v38, v4, v5
	v_cvt_pk_bf16_f32 v39, v2, v3
	s_waitcnt lgkmcnt(0)
	s_barrier
	ds_read_b128 v[56:59], v154
	ds_read_b128 v[2:5], v154 offset:32
	ds_read_b128 v[60:63], v154 offset:512
	s_mov_b32 s4, 0x358637bd
	v_cvt_pk_bf16_f32 v33, v20, v21
	v_mov_b64_e32 v[20:21], s[4:5]
	v_cvt_pk_bf16_f32 v7, v6, v7
	s_waitcnt lgkmcnt(0)
	v_pk_add_f32 v[36:37], v[56:57], v[60:61]
	v_cvt_pk_bf16_f32 v9, v8, v9
	v_pk_fma_f32 v[36:37], v[36:37], s[22:23], v[20:21] op_sel_hi:[1,0,0]
	v_cvt_pk_bf16_f32 v13, v12, v13
	v_mul_f32_e32 v6, 0x4b800000, v36
	v_cmp_gt_f32_e64 s[6:7], s92, v36
	v_cmp_gt_f32_e64 s[4:5], s92, v37
	v_cvt_pk_bf16_f32 v11, v10, v11
	v_cndmask_b32_e64 v6, v36, v6, s[6:7]
	v_rsq_f32_e32 v6, v6
	v_cvt_pk_bf16_f32 v15, v14, v15
	v_cvt_pk_bf16_f32 v31, v30, v31
	v_cvt_pk_bf16_f32 v23, v22, v23
	v_mul_f32_e32 v8, 0x45800000, v6
	v_cndmask_b32_e64 v12, v6, v8, s[6:7]
	v_mul_f32_e32 v6, 0x4b800000, v37
	v_cndmask_b32_e64 v6, v37, v6, s[4:5]
	v_rsq_f32_e32 v6, v6
	v_pk_add_f32 v[36:37], v[58:59], v[62:63]
	ds_read_b128 v[56:59], v154 offset:544
	v_pk_fma_f32 v[36:37], v[36:37], s[22:23], v[20:21] op_sel_hi:[1,0,0]
	v_mul_f32_e32 v8, 0x45800000, v6
	v_cndmask_b32_e64 v8, v6, v8, s[4:5]
	v_mul_f32_e32 v6, 0x4b800000, v36
	v_cmp_gt_f32_e64 s[6:7], s92, v36
	v_cmp_gt_f32_e64 s[4:5], s92, v37
	s_waitcnt lgkmcnt(0)
	v_pk_add_f32 v[2:3], v[2:3], v[56:57]
	v_cndmask_b32_e64 v6, v36, v6, s[6:7]
	v_rsq_f32_e32 v6, v6
	v_pk_fma_f32 v[2:3], v[2:3], s[22:23], v[20:21] op_sel_hi:[1,0,0]
	v_pk_add_f32 v[4:5], v[4:5], v[58:59]
	ds_read_b128 v[56:59], v154 offset:64
	ds_read_b128 v[60:63], v154 offset:576
	v_mul_f32_e32 v10, 0x45800000, v6
	v_cndmask_b32_e64 v10, v6, v10, s[6:7]
	v_mul_f32_e32 v6, 0x4b800000, v37
	v_cndmask_b32_e64 v6, v37, v6, s[4:5]
	v_rsq_f32_e32 v6, v6
	v_cmp_gt_f32_e64 s[6:7], s92, v2
	v_pk_fma_f32 v[4:5], v[4:5], s[22:23], v[20:21] op_sel_hi:[1,0,0]
	v_cvt_pk_bf16_f32 v25, v24, v25
	v_mul_f32_e32 v14, 0x45800000, v6
	v_cndmask_b32_e64 v6, v6, v14, s[4:5]
	v_mul_f32_e32 v14, 0x4b800000, v2
	v_cndmask_b32_e64 v2, v2, v14, s[6:7]
	v_rsq_f32_e32 v2, v2
	v_cmp_gt_f32_e64 s[4:5], s92, v3
	v_cvt_pk_bf16_f32 v27, v26, v27
	v_cvt_pk_bf16_f32 v17, v16, v17
	v_mul_f32_e32 v14, 0x45800000, v2
	v_cndmask_b32_e64 v2, v2, v14, s[6:7]
	v_mul_f32_e32 v14, 0x4b800000, v3
	v_cndmask_b32_e64 v3, v3, v14, s[4:5]
	v_rsq_f32_e32 v3, v3
	v_cmp_gt_f32_e64 s[6:7], s92, v4
	v_cvt_pk_bf16_f32 v29, v28, v29
	v_cvt_pk_bf16_f32 v19, v18, v19
	v_mul_f32_e32 v14, 0x45800000, v3
	v_cndmask_b32_e64 v14, v3, v14, s[4:5]
	v_mul_f32_e32 v3, 0x4b800000, v4
	v_cndmask_b32_e64 v3, v4, v3, s[6:7]
	v_rsq_f32_e32 v3, v3
	v_cmp_gt_f32_e64 s[4:5], s92, v5
	v_readlane_b32 s64, v235, 16
	v_readlane_b32 s68, v235, 20
	v_mul_f32_e32 v4, 0x45800000, v3
	v_cndmask_b32_e64 v30, v3, v4, s[6:7]
	v_mul_f32_e32 v3, 0x4b800000, v5
	v_cndmask_b32_e64 v3, v5, v3, s[4:5]
	v_rsq_f32_e32 v3, v3
	v_readlane_b32 s69, v235, 21
	v_cvt_pk_bf16_f32 v40, v34, v35
	v_cvt_pk_bf16_f32 v34, v116, v117
	v_mul_f32_e32 v4, 0x45800000, v3
	v_cndmask_b32_e64 v22, v3, v4, s[4:5]
	s_waitcnt lgkmcnt(0)
	v_pk_add_f32 v[4:5], v[56:57], v[60:61]
	v_lshlrev_b32_e32 v36, 16, v34
	v_pk_fma_f32 v[4:5], v[4:5], s[22:23], v[20:21] op_sel_hi:[1,0,0]
	v_and_b32_e32 v37, 0xffff0000, v34
	v_mul_f32_e32 v3, 0x4b800000, v4
	v_cmp_gt_f32_e64 s[6:7], s92, v4
	v_cmp_gt_f32_e64 s[4:5], s92, v5
	v_pk_mul_f32 v[36:37], v[12:13], v[36:37] op_sel_hi:[0,1]
	v_cndmask_b32_e64 v3, v4, v3, s[6:7]
	v_rsq_f32_e32 v3, v3
	v_cvt_pk_bf16_f32 v55, v118, v119
	v_cvt_pk_bf16_f32 v54, v120, v121
	v_cvt_pk_bf16_f32 v53, v122, v123
	v_mul_f32_e32 v4, 0x45800000, v3
	v_cndmask_b32_e64 v32, v3, v4, s[6:7]
	v_mul_f32_e32 v3, 0x4b800000, v5
	v_cndmask_b32_e64 v3, v5, v3, s[4:5]
	v_rsq_f32_e32 v3, v3
	v_cvt_pk_bf16_f32 v52, v124, v125
	v_cvt_pk_bf16_f32 v51, v126, v127
	v_cvt_pk_bf16_f32 v50, v128, v129
	v_mul_f32_e32 v4, 0x45800000, v3
	v_cndmask_b32_e64 v24, v3, v4, s[4:5]
	v_pk_add_f32 v[4:5], v[58:59], v[62:63]
	ds_read_b128 v[56:59], v154 offset:96
	ds_read_b128 v[60:63], v154 offset:608
	v_pk_fma_f32 v[4:5], v[4:5], s[22:23], v[20:21] op_sel_hi:[1,0,0]
	v_cvt_pk_bf16_f32 v49, v130, v131
	v_mul_f32_e32 v3, 0x4b800000, v4
	v_cmp_gt_f32_e64 s[6:7], s92, v4
	v_cmp_gt_f32_e64 s[4:5], s92, v5
	v_cvt_pk_bf16_f32 v48, v132, v133
	v_cndmask_b32_e64 v3, v4, v3, s[6:7]
	v_rsq_f32_e32 v3, v3
	v_cvt_pk_bf16_f32 v47, v134, v135
	v_cvt_pk_bf16_f32 v46, v136, v137
	v_cvt_pk_bf16_f32 v45, v138, v139
	v_mul_f32_e32 v4, 0x45800000, v3
	v_cndmask_b32_e64 v26, v3, v4, s[6:7]
	v_mul_f32_e32 v3, 0x4b800000, v5
	v_cndmask_b32_e64 v3, v5, v3, s[4:5]
	v_rsq_f32_e32 v3, v3
	v_cvt_pk_bf16_f32 v44, v140, v141
	v_cvt_pk_bf16_f32 v43, v142, v143
	v_cvt_pk_bf16_f32 v42, v144, v145
	v_mul_f32_e32 v4, 0x45800000, v3
	v_cndmask_b32_e64 v16, v3, v4, s[4:5]
	s_waitcnt lgkmcnt(0)
	v_pk_add_f32 v[4:5], v[56:57], v[60:61]
	v_cvt_pk_bf16_f32 v41, v146, v147
	v_pk_fma_f32 v[4:5], v[4:5], s[22:23], v[20:21] op_sel_hi:[1,0,0]
	v_readlane_b32 s65, v235, 17
	v_mul_f32_e32 v3, 0x4b800000, v4
	v_cmp_gt_f32_e64 s[6:7], s92, v4
	v_cmp_gt_f32_e64 s[4:5], s92, v5
	v_readlane_b32 s66, v235, 18
	v_cndmask_b32_e64 v3, v4, v3, s[6:7]
	v_rsq_f32_e32 v3, v3
	v_readlane_b32 s67, v235, 19
	v_readlane_b32 s70, v235, 22
	v_readlane_b32 s71, v235, 23
	v_mul_f32_e32 v4, 0x45800000, v3
	v_cndmask_b32_e64 v28, v3, v4, s[6:7]
	v_mul_f32_e32 v3, 0x4b800000, v5
	v_cndmask_b32_e64 v3, v5, v3, s[4:5]
	v_rsq_f32_e32 v3, v3
	v_readlane_b32 s72, v235, 24
	v_readlane_b32 s73, v235, 25
	v_readlane_b32 s74, v235, 26
	v_mul_f32_e32 v4, 0x45800000, v3
	v_cndmask_b32_e64 v18, v3, v4, s[4:5]
	v_pk_add_f32 v[4:5], v[58:59], v[62:63]
	v_readlane_b32 s75, v235, 27
	v_pk_fma_f32 v[4:5], v[4:5], s[22:23], v[20:21] op_sel_hi:[1,0,0]
	v_readlane_b32 s76, v235, 28
	v_mul_f32_e32 v3, 0x4b800000, v4
	v_cmp_gt_f32_e64 s[6:7], s92, v4
	v_cmp_gt_f32_e64 s[4:5], s92, v5
	v_readlane_b32 s77, v235, 29
	v_cndmask_b32_e64 v3, v4, v3, s[6:7]
	v_rsq_f32_e32 v3, v3
	v_readlane_b32 s78, v235, 30
	v_readlane_b32 s79, v235, 31
	v_mul_f32_e32 v4, 0x45800000, v3
	v_cndmask_b32_e64 v20, v3, v4, s[6:7]
	v_mul_f32_e32 v3, 0x4b800000, v5
	v_cndmask_b32_e64 v3, v5, v3, s[4:5]
	v_rsq_f32_e32 v3, v3
	s_nop 0
	v_mul_f32_e32 v4, 0x45800000, v3
	v_cndmask_b32_e64 v4, v3, v4, s[4:5]
	v_or_b32_e32 v3, 0x200, v115
	v_mov_b32_e32 v115, v111
	s_waitcnt vmcnt(0)
	v_mov_b32_e32 v34, v88
	v_mov_b32_e32 v35, v89
	s_nop 0
	v_readlane_b32 s4, v235, 44
	v_readlane_b32 s6, v235, 46
	v_readlane_b32 s7, v235, 47
	v_add_lshl_u32 v5, v3, v114, 1
	v_readlane_b32 s5, v235, 45
	s_mov_b32 s6, s10
	s_mov_b32 s7, s11
	s_mov_b64 s[24:25], s[4:5]
	v_writelane_b32 v235, s24, 44
	s_waitcnt vmcnt(0)
	s_mov_b64 s[100:101], exec
	s_and_b64 exec, exec, s[0:1]
	s_cbranch_execz .Lyoff_wb_skip
	buffer_wbl2 sc1
; __device__ __forceinline__ void yoff_unit(const float* d_skip, const float* gnorm, LAS unsigned char* ldsb, int unit, const bf16* XACT, const bf16* PROJ, const float* ACS, const bf16* PREVT,
;                                           const bf16* YD, bf16* MIXB, int lane, int wave) {
;     ...
;     for (int hsel = 0; hsel < 2; ++hsel) {
;         const unsigned col = (unsigned)((g * 4 + 2 * hpair + hsel) * 64 + 2 * r); const float gn0 = gnorm[col], gn1 = gnorm[col + 1];
;         const unsigned voB = (tb * 1024u + 512u + col) * 2u;
; #pragma unroll
;         for (int i = 0; i < 16; ++i) { const unsigned w = ypk[hsel][i]; const float sn = ssq[i];
;             __builtin_amdgcn_raw_buffer_store_b32(pkbf(__uint_as_float(w << 16) * sn * gn0, __uint_as_float(w & 0xffff0000u) * sn * gn1), rsB, (int)voB, ((i & 3) + 8 * (i >> 2)) * 2048, 16); }
.Lyoff_wb_skip:
	s_mov_b64 exec, s[100:101]
	s_nop 0
	s_nop 0
	v_pk_mul_f32 v[36:37], v[36:37], v[34:35]
	s_nop 0
	v_cvt_pk_bf16_f32 v21, v36, v37
	v_lshlrev_b32_e32 v36, 16, v55
	v_and_b32_e32 v37, 0xffff0000, v55
	v_pk_mul_f32 v[36:37], v[8:9], v[36:37] op_sel_hi:[0,1]
	v_pk_mul_f32 v[36:37], v[36:37], v[34:35]
	buffer_store_dword v21, v5, s[4:7], 0 offen sc1
	v_cvt_pk_bf16_f32 v21, v36, v37
	v_lshlrev_b32_e32 v36, 16, v54
	v_and_b32_e32 v37, 0xffff0000, v54
	v_pk_mul_f32 v[36:37], v[10:11], v[36:37] op_sel_hi:[0,1]
	v_pk_mul_f32 v[36:37], v[36:37], v[34:35]
	buffer_store_dword v21, v5, s[4:7], s46 offen sc1
	v_cvt_pk_bf16_f32 v21, v36, v37
	v_lshlrev_b32_e32 v36, 16, v53
	v_and_b32_e32 v37, 0xffff0000, v53
	v_pk_mul_f32 v[36:37], v[6:7], v[36:37] op_sel_hi:[0,1]
	v_pk_mul_f32 v[36:37], v[36:37], v[34:35]
	buffer_store_dword v21, v5, s[4:7], s48 offen sc1
	v_cvt_pk_bf16_f32 v21, v36, v37
	v_lshlrev_b32_e32 v36, 16, v52
	v_and_b32_e32 v37, 0xffff0000, v52
	v_pk_mul_f32 v[36:37], v[2:3], v[36:37] op_sel_hi:[0,1]
	v_pk_mul_f32 v[36:37], v[36:37], v[34:35]
	buffer_store_dword v21, v5, s[4:7], s56 offen sc1
	v_cvt_pk_bf16_f32 v21, v36, v37
	v_lshlrev_b32_e32 v36, 16, v51
	v_and_b32_e32 v37, 0xffff0000, v51
	v_pk_mul_f32 v[36:37], v[14:15], v[36:37] op_sel_hi:[0,1]
	v_pk_mul_f32 v[36:37], v[36:37], v[34:35]
	buffer_store_dword v21, v5, s[4:7], s62 offen sc1
	v_cvt_pk_bf16_f32 v21, v36, v37
	v_lshlrev_b32_e32 v36, 16, v50
	v_and_b32_e32 v37, 0xffff0000, v50
	v_pk_mul_f32 v[36:37], v[30:31], v[36:37] op_sel_hi:[0,1]
	v_pk_mul_f32 v[36:37], v[36:37], v[34:35]
	buffer_store_dword v21, v5, s[4:7], s82 offen sc1
	v_cvt_pk_bf16_f32 v21, v36, v37
	v_lshlrev_b32_e32 v36, 16, v49
	v_and_b32_e32 v37, 0xffff0000, v49
	v_pk_mul_f32 v[36:37], v[22:23], v[36:37] op_sel_hi:[0,1]
	v_pk_mul_f32 v[36:37], v[36:37], v[34:35]
	buffer_store_dword v21, v5, s[4:7], s93 offen sc1
	v_cvt_pk_bf16_f32 v21, v36, v37
	v_lshlrev_b32_e32 v36, 16, v48
	v_and_b32_e32 v37, 0xffff0000, v48
	v_pk_mul_f32 v[36:37], v[32:33], v[36:37] op_sel_hi:[0,1]
	v_pk_mul_f32 v[36:37], v[36:37], v[34:35]
	buffer_store_dword v21, v5, s[4:7], s20 offen sc1
	v_cvt_pk_bf16_f32 v21, v36, v37
	v_lshlrev_b32_e32 v36, 16, v47
	v_and_b32_e32 v37, 0xffff0000, v47
	v_pk_mul_f32 v[36:37], v[24:25], v[36:37] op_sel_hi:[0,1]
	v_pk_mul_f32 v[36:37], v[36:37], v[34:35]
	buffer_store_dword v21, v5, s[4:7], s84 offen sc1
	v_cvt_pk_bf16_f32 v21, v36, v37
	v_lshlrev_b32_e32 v36, 16, v46
	v_and_b32_e32 v37, 0xffff0000, v46
	v_pk_mul_f32 v[36:37], v[26:27], v[36:37] op_sel_hi:[0,1]
	v_pk_mul_f32 v[36:37], v[36:37], v[34:35]
	buffer_store_dword v21, v5, s[4:7], s28 offen sc1
	v_cvt_pk_bf16_f32 v21, v36, v37
	v_lshlrev_b32_e32 v36, 16, v45
	v_and_b32_e32 v37, 0xffff0000, v45
	v_pk_mul_f32 v[36:37], v[16:17], v[36:37] op_sel_hi:[0,1]
	v_pk_mul_f32 v[36:37], v[34:35], v[36:37]
	buffer_store_dword v21, v5, s[4:7], s63 offen sc1
	v_cvt_pk_bf16_f32 v21, v36, v37
	v_lshlrev_b32_e32 v36, 16, v44
	v_and_b32_e32 v37, 0xffff0000, v44
	v_pk_mul_f32 v[36:37], v[28:29], v[36:37] op_sel_hi:[0,1]
	v_pk_mul_f32 v[36:37], v[34:35], v[36:37]
	buffer_store_dword v21, v5, s[4:7], s37 offen sc1
	v_cvt_pk_bf16_f32 v21, v36, v37
	v_lshlrev_b32_e32 v36, 16, v43
	v_and_b32_e32 v37, 0xffff0000, v43
	v_pk_mul_f32 v[36:37], v[18:19], v[36:37] op_sel_hi:[0,1]
	v_pk_mul_f32 v[36:37], v[34:35], v[36:37]
	buffer_store_dword v21, v5, s[4:7], s40 offen sc1
	v_cvt_pk_bf16_f32 v21, v36, v37
	v_lshlrev_b32_e32 v36, 16, v42
	v_and_b32_e32 v37, 0xffff0000, v42
	v_pk_mul_f32 v[36:37], v[20:21], v[36:37] op_sel_hi:[0,1]
	v_pk_mul_f32 v[36:37], v[34:35], v[36:37]
	buffer_store_dword v21, v5, s[4:7], s43 offen sc1
	v_cvt_pk_bf16_f32 v21, v36, v37
	v_lshlrev_b32_e32 v36, 16, v41
	v_and_b32_e32 v37, 0xffff0000, v41
	v_pk_mul_f32 v[36:37], v[4:5], v[36:37] op_sel_hi:[0,1]
	v_pk_mul_f32 v[34:35], v[34:35], v[36:37]
	buffer_store_dword v21, v5, s[4:7], s47 offen sc1
	v_cvt_pk_bf16_f32 v21, v34, v35
	buffer_store_dword v21, v5, s[4:7], s59 offen sc1
	v_mov_b32_e32 v34, v90
	v_mov_b32_e32 v35, v91
	s_nop 0
	s_nop 0
	v_lshlrev_b32_e32 v36, 16, v40
	v_and_b32_e32 v37, 0xffff0000, v40
	v_pk_mul_f32 v[36:37], v[12:13], v[36:37] op_sel_hi:[0,1]
	v_add_lshl_u32 v5, v3, v110, 1
	v_writelane_b32 v235, s25, 45
	v_writelane_b32 v235, s26, 46
	v_writelane_b32 v235, s27, 47
	s_nop 0
	v_pk_mul_f32 v[36:37], v[36:37], v[34:35]
; __device__ __forceinline__ unsigned xb_add(unsigned* p, unsigned v) { return __hip_atomic_fetch_add(p, v, __ATOMIC_RELAXED, __HIP_MEMORY_SCOPE_AGENT); }
; __device__ __forceinline__ void yoff_unit(const float* d_skip, const float* gnorm, LAS unsigned char* ldsb, int unit, const bf16* XACT, const bf16* PROJ, const float* ACS, const bf16* PREVT,
;                                           const bf16* YD, bf16* MIXB, int lane, int wave) {
;     ...
;         for (int i = 0; i < 16; ++i) { const unsigned w = ypk[hsel][i]; const float sn = ssq[i];
;             __builtin_amdgcn_raw_buffer_store_b32(pkbf(__uint_as_float(w << 16) * sn * gn0, __uint_as_float(w & 0xffff0000u) * sn * gn1), rsB, (int)voB, ((i & 3) + 8 * (i >> 2)) * 2048, 16); }
;     }
;     __syncthreads();
; __global__ void __launch_bounds__(NTHR, 2) k_main(Args a) {
;     ...
;             asm volatile("s_waitcnt vmcnt(0)" ::: "memory");
;             __syncthreads();
;             if (tid == 0) { __builtin_amdgcn_fence(__ATOMIC_RELEASE, "agent"); asm volatile("s_waitcnt vmcnt(0)" ::: "memory"); (void)xb_add(&((unsigned*)ws)[10240 + 16 * (u >> 2)], 1u); (void)xb_add(&((unsigned*)ws)[14336], 1u); }
	s_nop 0
	v_cvt_pk_bf16_f32 v3, v36, v37
	v_lshlrev_b32_e32 v36, 16, v39
	v_and_b32_e32 v37, 0xffff0000, v39
	v_pk_mul_f32 v[36:37], v[8:9], v[36:37] op_sel_hi:[0,1]
	v_pk_mul_f32 v[36:37], v[36:37], v[34:35]
	buffer_store_dword v3, v5, s[4:7], 0 offen sc1
	v_cvt_pk_bf16_f32 v3, v36, v37
	v_lshlrev_b32_e32 v36, 16, v19
	v_and_b32_e32 v37, 0xffff0000, v19
	v_pk_mul_f32 v[36:37], v[10:11], v[36:37] op_sel_hi:[0,1]
	v_pk_mul_f32 v[36:37], v[36:37], v[34:35]
	buffer_store_dword v3, v5, s[4:7], s46 offen sc1
	v_cvt_pk_bf16_f32 v3, v36, v37
	v_lshlrev_b32_e32 v36, 16, v38
	v_and_b32_e32 v37, 0xffff0000, v38
	v_pk_mul_f32 v[36:37], v[6:7], v[36:37] op_sel_hi:[0,1]
	v_pk_mul_f32 v[36:37], v[36:37], v[34:35]
	buffer_store_dword v3, v5, s[4:7], s48 offen sc1
	v_cvt_pk_bf16_f32 v3, v36, v37
	v_lshlrev_b32_e32 v36, 16, v33
	v_and_b32_e32 v37, 0xffff0000, v33
	buffer_store_dword v3, v5, s[4:7], s56 offen sc1
	v_pk_mul_f32 v[2:3], v[2:3], v[36:37] op_sel_hi:[0,1]
	v_pk_mul_f32 v[2:3], v[2:3], v[34:35]
	s_nop 0
	v_cvt_pk_bf16_f32 v2, v2, v3
	buffer_store_dword v2, v5, s[4:7], s62 offen sc1
	v_lshlrev_b32_e32 v2, 16, v7
	v_and_b32_e32 v3, 0xffff0000, v7
	v_pk_mul_f32 v[2:3], v[14:15], v[2:3] op_sel_hi:[0,1]
	v_pk_mul_f32 v[2:3], v[2:3], v[34:35]
	s_nop 0
	v_cvt_pk_bf16_f32 v2, v2, v3
	buffer_store_dword v2, v5, s[4:7], s82 offen sc1
	v_lshlrev_b32_e32 v2, 16, v23
	v_and_b32_e32 v3, 0xffff0000, v23
	v_pk_mul_f32 v[2:3], v[30:31], v[2:3] op_sel_hi:[0,1]
	v_pk_mul_f32 v[2:3], v[2:3], v[34:35]
	s_nop 0
	v_cvt_pk_bf16_f32 v2, v2, v3
	buffer_store_dword v2, v5, s[4:7], s93 offen sc1
	v_lshlrev_b32_e32 v2, 16, v9
	v_and_b32_e32 v3, 0xffff0000, v9
	v_pk_mul_f32 v[2:3], v[22:23], v[2:3] op_sel_hi:[0,1]
	v_pk_mul_f32 v[2:3], v[2:3], v[34:35]
	s_nop 0
	v_cvt_pk_bf16_f32 v2, v2, v3
	buffer_store_dword v2, v5, s[4:7], s20 offen sc1
	v_lshlrev_b32_e32 v2, 16, v25
	v_and_b32_e32 v3, 0xffff0000, v25
	v_pk_mul_f32 v[2:3], v[32:33], v[2:3] op_sel_hi:[0,1]
	v_pk_mul_f32 v[2:3], v[2:3], v[34:35]
	s_nop 0
	v_cvt_pk_bf16_f32 v2, v2, v3
	buffer_store_dword v2, v5, s[4:7], s84 offen sc1
	v_lshlrev_b32_e32 v2, 16, v11
	v_and_b32_e32 v3, 0xffff0000, v11
	v_pk_mul_f32 v[2:3], v[24:25], v[2:3] op_sel_hi:[0,1]
	v_pk_mul_f32 v[2:3], v[2:3], v[34:35]
	s_nop 0
	v_cvt_pk_bf16_f32 v2, v2, v3
	buffer_store_dword v2, v5, s[4:7], s28 offen sc1
	v_lshlrev_b32_e32 v2, 16, v27
	v_and_b32_e32 v3, 0xffff0000, v27
	v_pk_mul_f32 v[2:3], v[26:27], v[2:3] op_sel_hi:[0,1]
	v_pk_mul_f32 v[2:3], v[2:3], v[34:35]
	s_nop 0
	v_cvt_pk_bf16_f32 v2, v2, v3
	buffer_store_dword v2, v5, s[4:7], s63 offen sc1
	v_lshlrev_b32_e32 v2, 16, v13
	v_and_b32_e32 v3, 0xffff0000, v13
	v_pk_mul_f32 v[2:3], v[16:17], v[2:3] op_sel_hi:[0,1]
	v_pk_mul_f32 v[2:3], v[2:3], v[34:35]
	s_nop 0
	v_cvt_pk_bf16_f32 v2, v2, v3
	buffer_store_dword v2, v5, s[4:7], s37 offen sc1
	v_lshlrev_b32_e32 v2, 16, v29
	v_and_b32_e32 v3, 0xffff0000, v29
	v_pk_mul_f32 v[2:3], v[28:29], v[2:3] op_sel_hi:[0,1]
	v_pk_mul_f32 v[2:3], v[2:3], v[34:35]
	s_nop 0
	v_cvt_pk_bf16_f32 v2, v2, v3
	buffer_store_dword v2, v5, s[4:7], s40 offen sc1
	v_lshlrev_b32_e32 v2, 16, v15
	v_and_b32_e32 v3, 0xffff0000, v15
	v_pk_mul_f32 v[2:3], v[18:19], v[2:3] op_sel_hi:[0,1]
	v_pk_mul_f32 v[2:3], v[2:3], v[34:35]
	s_nop 0
	v_cvt_pk_bf16_f32 v2, v2, v3
	buffer_store_dword v2, v5, s[4:7], s43 offen sc1
	v_lshlrev_b32_e32 v2, 16, v31
	v_and_b32_e32 v3, 0xffff0000, v31
	v_pk_mul_f32 v[2:3], v[20:21], v[2:3] op_sel_hi:[0,1]
	v_pk_mul_f32 v[2:3], v[2:3], v[34:35]
	s_nop 0
	v_cvt_pk_bf16_f32 v2, v2, v3
	buffer_store_dword v2, v5, s[4:7], s47 offen sc1
	v_lshlrev_b32_e32 v2, 16, v17
	v_and_b32_e32 v3, 0xffff0000, v17
	v_pk_mul_f32 v[2:3], v[4:5], v[2:3] op_sel_hi:[0,1]
	v_pk_mul_f32 v[2:3], v[2:3], v[34:35]
	s_nop 0
	v_cvt_pk_bf16_f32 v2, v2, v3
	buffer_store_dword v2, v5, s[4:7], s59 offen sc1
	s_barrier
	s_waitcnt vmcnt(0)
	s_barrier
	s_and_saveexec_b64 s[6:7], s[0:1]
	s_cbranch_execz .LBB0_465
	s_mov_b64 s[24:25], exec
	s_waitcnt vmcnt(0)
	s_waitcnt vmcnt(0)
	v_mbcnt_lo_u32_b32 v2, s24, 0
	v_mbcnt_hi_u32_b32 v2, s25, v2
	v_cmp_eq_u32_e64 s[4:5], 0, v2
	s_and_saveexec_b64 s[26:27], s[4:5]
	s_cbranch_execz .LBB0_471
	s_and_b32 s4, s30, -16
	s_ashr_i32 s5, s4, 31
	s_lshl_b64 s[4:5], s[4:5], 2
	s_add_u32 s4, s90, s4
	s_addc_u32 s5, s91, s5
	s_bcnt1_i32_b64 s24, s[24:25]
	v_mov_b32_e32 v2, s24
	global_atomic_add v162, v2, s[4:5]

; #define LAS __attribute__((address_space(3)))
; __global__ void __launch_bounds__(NTHR, 2) k_main(Args a) {
;     ...
;             for (int i = tid; i < 2 * 128 * 8; i += NTHR) {
;                 const int pc = i & 7, key = (i >> 3) & 127, hf = (i >> 10) & 1, hl = i >> 11;
;                 *(LAS v4u*)(KHL + ((hl * 2 + hf) * 128 + key) * 72 + pc * 8) = *(const v4u*)((hl ? KL : KH) + (size_t)(hf * 128 + key) * 64 + pc * 8);
;             }
.LBB0_665:
	v_mov_b32_e32 v20, s53
	v_mov_b32_e32 v21, s49
	v_mov_b32_e32 v22, s52
	v_mov_b32_e32 v23, s48
	v_lshlrev_b32_e32 v24, 4, v19
	v_cmp_gt_u32_e32 vcc, s54, v19
	v_lshlrev_b32_e32 v25, 1, v18
	v_and_b32_e32 v82, 0x7f80, v24
	v_cndmask_b32_e32 v21, v20, v21, vcc
	v_cndmask_b32_e32 v20, v22, v23, vcc
	v_lshl_add_u64 v[20:21], v[20:21], 0, v[82:83]
	v_and_b32_e32 v82, 0x70, v25
	v_lshl_add_u64 v[20:21], v[20:21], 0, v[82:83]
	global_load_dwordx4 v[162:165], v[20:21], off
	v_lshrrev_b32_e32 v24, 3, v19
	v_mul_lo_u32 v24, v24, s56
	v_add3_u32 v178, 0, v24, v82
	v_add_u32_e32 v19, 0x200, v19
	v_add_u32_e32 v18, 0x1000, v18
	v_mov_b32_e32 v20, s53
	v_mov_b32_e32 v21, s49
	v_mov_b32_e32 v22, s52
	v_mov_b32_e32 v23, s48
	v_lshlrev_b32_e32 v24, 4, v19
	v_cmp_gt_u32_e32 vcc, s54, v19
	v_lshlrev_b32_e32 v25, 1, v18
	v_and_b32_e32 v82, 0x7f80, v24
	v_cndmask_b32_e32 v21, v20, v21, vcc
	v_cndmask_b32_e32 v20, v22, v23, vcc
	v_lshl_add_u64 v[20:21], v[20:21], 0, v[82:83]
	v_and_b32_e32 v82, 0x70, v25
	v_lshl_add_u64 v[20:21], v[20:21], 0, v[82:83]
	global_load_dwordx4 v[166:169], v[20:21], off
	v_lshrrev_b32_e32 v24, 3, v19
	v_mul_lo_u32 v24, v24, s56
	v_add3_u32 v179, 0, v24, v82
	v_add_u32_e32 v19, 0x200, v19
	v_add_u32_e32 v18, 0x1000, v18
	v_mov_b32_e32 v20, s53
	v_mov_b32_e32 v21, s49
	v_mov_b32_e32 v22, s52
	v_mov_b32_e32 v23, s48
	v_lshlrev_b32_e32 v24, 4, v19
	v_cmp_gt_u32_e32 vcc, s54, v19
	v_lshlrev_b32_e32 v25, 1, v18
	v_and_b32_e32 v82, 0x7f80, v24
	v_cndmask_b32_e32 v21, v20, v21, vcc
	v_cndmask_b32_e32 v20, v22, v23, vcc
	v_lshl_add_u64 v[20:21], v[20:21], 0, v[82:83]
	v_and_b32_e32 v82, 0x70, v25
	v_lshl_add_u64 v[20:21], v[20:21], 0, v[82:83]
	global_load_dwordx4 v[170:173], v[20:21], off
	v_lshrrev_b32_e32 v24, 3, v19
	v_mul_lo_u32 v24, v24, s56
	v_add3_u32 v180, 0, v24, v82
	v_add_u32_e32 v19, 0x200, v19
	v_add_u32_e32 v18, 0x1000, v18
	v_mov_b32_e32 v20, s53
	v_mov_b32_e32 v21, s49
	v_mov_b32_e32 v22, s52
	v_mov_b32_e32 v23, s48
	v_lshlrev_b32_e32 v24, 4, v19
	v_cmp_gt_u32_e32 vcc, s54, v19
	v_lshlrev_b32_e32 v25, 1, v18
	v_and_b32_e32 v82, 0x7f80, v24
	v_cndmask_b32_e32 v21, v20, v21, vcc
	v_cndmask_b32_e32 v20, v22, v23, vcc
	v_lshl_add_u64 v[20:21], v[20:21], 0, v[82:83]
	v_and_b32_e32 v82, 0x70, v25
	v_lshl_add_u64 v[20:21], v[20:21], 0, v[82:83]
	global_load_dwordx4 v[174:177], v[20:21], off
	v_lshrrev_b32_e32 v24, 3, v19
	v_mul_lo_u32 v24, v24, s56
	v_add3_u32 v181, 0, v24, v82
	v_add_u32_e32 v19, 0x200, v19
	v_add_u32_e32 v18, 0x1000, v18
	s_waitcnt vmcnt(0)
	ds_write_b128 v178, v[162:165]
	ds_write_b128 v179, v[166:169]
	ds_write_b128 v180, v[170:173]
	ds_write_b128 v181, v[174:177]
	s_nop 0
	s_nop 0
	s_nop 0
	s_nop 0
	s_nop 0
	s_nop 0
	s_nop 0
	s_nop 0
	s_nop 0
	s_nop 0
	s_nop 0
	s_nop 0
	s_nop 0
	s_nop 0
	s_nop 0
	s_nop 0
	s_nop 0
	s_nop 0
	s_nop 0
	s_nop 0
	s_nop 0
